# P10-epilogue-all-eight-blocks-hand-rewritten-plus-single-acc-zeroing
# speedup vs baseline: 1.0161x; 1.0029x over previous
;     template <bool SAMPLE> __device__ __forceinline__ void body(const pg8::f32x4 (&acc)[2][2][4][2], const pg8::Unit& u, int wr, int fr, int cl0_, int acol0, LAS float* CW, LAS float* BD, LAS float* RSL) const {
;     ...
;                         const int cl = bj * 128 + cl0 + 4 * n, gcol = bj * DFF + acol0 + cl0 + 4 * n; const f32x4 x = acc[ai][bj][m][n] * rs;
;                         f32x4 s1, s2;
; #pragma unroll
;                         for (int i = 0; i < 4; ++i) { s1[i] = dpp_ror1(x[i]); s2[i] = dpp_ror2(x[i]); }
;                         if (SAMPLE) { const int t = fro & 3; const float* sp = state_conv + (size_t)((row - MP) >> 2) * 2 * UPW + gcol;
;                             const f32x4 S0 = *(const GAS f32x4*)sp, S1 = *(const GAS f32x4*)(sp + UPW);
; #pragma unroll
;                             for (int i = 0; i < 4; ++i) { s1[i] = (t >= 1) ? s1[i] : S1[i]; s2[i] = (t >= 2) ? s2[i] : (t == 1 ? S1[i] : S0[i]); }
;                             if (t >= 2) *(GAS f32x4*)(out + O_CVS + ((size_t)((row - MP) >> 2) * 2 + (t - 2)) * UPW + gcol) = x;
;                         } else if (m > 0) { const f32x4 xp = acc[ai][bj][m > 0 ? m - 1 : 0][n] * RSL[rl - 16];
; #pragma unroll
;                             for (int i = 0; i < 4; ++i) { s1[i] = dpp_ror1(fro == 15 ? xp[i] : x[i]); s2[i] = dpp_ror2(fro >= 14 ? xp[i] : x[i]); }
;                         } else { const int pb = (wr == 1) ? ai * 2 : 1;
;                             const int pr0 = (pb >> 1) * 128 + (pb & 1) * 64 + 62;
;                             const f32x4 b2 = *(const LAS f32x4*)(BD + (pb * 2 + 0) * 256 + cl) * RSL[pr0], b1 = *(const LAS f32x4*)(BD + (pb * 2 + 1) * 256 + cl) * RSL[pr0 + 1];
; #pragma unroll
;                             for (int i = 0; i < 4; ++i) { s1[i] = (fro >= 1) ? s1[i] : b1[i]; s2[i] = (fro >= 2) ? s2[i] : (fro == 1 ? b1[i] : b2[i]); }
;                         }
;                         const f32x4 w0 = *(const LAS f32x4*)(CW + cl), w1 = *(const LAS f32x4*)(CW + 256 + cl), w2 = *(const LAS f32x4*)(CW + 512 + cl), cb = *(const LAS f32x4*)(CW + 768 + cl);
;                         cv2[bj] = cb + s2 * w0 + s1 * w1 + x * w2;
;                         if (!SAMPLE && ai == 0 && m == 0) { if (rl < 2) { v2u w; w.x = cvt_pk_bf16(x[0], x[1]); w.y = cvt_pk_bf16(x[2], x[3]); *(GAS v2u*)(UPF + ((size_t)u.pm * 2 + rl) * UPW + gcol) = w; } }
.LBB0_2595:
	s_or_b64 exec, exec, s[0:1]
	s_waitcnt vmcnt(0) lgkmcnt(0)
	s_barrier
	s_ashr_i32 s37, s36, 31
	s_lshl_b32 s16, s28, 8
	s_cmp_lt_i32 s28, 64
	s_mov_b64 s[0:1], -1
	s_cbranch_scc0 .LBB0_2633
	s_add_i32 s17, 0, 0x23000
	v_readlane_b32 s0, v255, 37
	s_add_i32 s1, s17, s83
	v_readlane_b32 s8, v254, 15
	v_readlane_b32 s9, v254, 16
	s_ashr_i32 s29, s28, 31
	v_mov_b32_e32 v140, v198
	v_lshl_add_u32 v141, v198, 2, 0
	v_cmp_eq_u32_e64 s[4:5], 15, v199
	v_cmp_lt_i32_e64 s[2:3], 13, v199
	v_cmp_eq_u32_e64 s[6:7], 14, v199
	v_add_u32_e32 v158, s77, v199
	v_add_u32_e32 v159, s0, v141
	v_add_u32_e32 v141, 0x20000, v141
	v_lshl_add_u32 v138, v158, 2, s17
	v_mov_b32_e32 v168, s1
	ds_read_b32 v138, v138
	ds_read_b32 v170, v168 offset:252
	ds_read_b32 v168, v168 offset:248
	ds_read_b128 v[204:207], v141
	ds_read_b128 v[208:211], v141 offset:1024
	ds_read_b128 v[212:215], v141 offset:2048
	ds_read_b128 v[216:219], v141 offset:3072
	ds_read_b128 v[172:175], v159
	ds_read_b128 v[176:179], v159 offset:1024
	ds_read_b128 v[228:231], v141 offset:512
	ds_read_b128 v[232:235], v141 offset:1536
	ds_read_b128 v[236:239], v141 offset:2560
	ds_read_b128 v[240:243], v141 offset:3584
	ds_read_b128 v[244:247], v159 offset:512
	ds_read_b128 v[248:251], v159 offset:1536
	v_mov_b32_e32 v148, v158
	v_ashrrev_i32_e32 v149, 31, v158
	v_add_u32_e32 v146, s36, v198
	v_lshl_add_u64 v[152:153], s[28:29], 1, v[148:149]
	v_ashrrev_i32_e32 v147, 31, v146
	v_mov_b64_e32 v[154:155], s[8:9]
	v_add_u32_e32 v156, 0xb00, v146
	v_mad_u64_u32 v[154:155], s[24:25], v152, s87, v[154:155]
	v_ashrrev_i32_e32 v157, 31, v156
	v_mad_i32_i24 v155, v153, s87, v155
	v_cmp_gt_i32_e32 vcc, 2, v158
	v_lshl_add_u64 v[142:143], v[146:147], 1, v[154:155]
	v_lshl_add_u64 v[144:145], v[156:157], 1, v[154:155]
	s_waitcnt lgkmcnt(6)
	v_pk_mul_f32 v[134:135], v[126:127], v[138:139] op_sel_hi:[1,0]
	v_pk_mul_f32 v[136:137], v[128:129], v[138:139] op_sel_hi:[1,0]
	s_and_saveexec_b64 s[0:1], vcc
	s_cbranch_execz .Lmy_u00_0
	v_cvt_pk_bf16_f32 v150, v134, v135
	v_cvt_pk_bf16_f32 v151, v136, v137
	s_nop 0
	global_store_dwordx2 v[142:143], v[150:151], off
.Lmy_u00_0:
	s_or_b64 exec, exec, s[0:1]
	v_pk_mul_f32 v[172:173], v[172:173], v[168:169] op_sel_hi:[1,0]
	v_pk_mul_f32 v[174:175], v[174:175], v[168:169] op_sel_hi:[1,0]
	v_pk_mul_f32 v[176:177], v[176:177], v[170:171] op_sel_hi:[1,0]
	v_pk_mul_f32 v[178:179], v[178:179], v[170:171] op_sel_hi:[1,0]
	v_cndmask_b32_e64 v150, v176, v172, s[6:7]
	v_cndmask_b32_e64 v151, v177, v173, s[6:7]
	v_cndmask_b32_e64 v152, v178, v174, s[6:7]
	v_cndmask_b32_e64 v153, v179, v175, s[6:7]
	v_cndmask_b32_e64 v154, v134, v150, s[4:5]
	v_cndmask_b32_e64 v155, v135, v151, s[4:5]
	v_cndmask_b32_e64 v156, v136, v152, s[4:5]
	v_cndmask_b32_e64 v157, v137, v153, s[4:5]
	v_cndmask_b32_e64 v150, v134, v150, s[2:3]
	v_cndmask_b32_e64 v151, v135, v151, s[2:3]
	v_cndmask_b32_e64 v152, v136, v152, s[2:3]
	v_cndmask_b32_e64 v153, v137, v153, s[2:3]
	v_fmac_f32_dpp v216, v150, v204 row_ror:2 row_mask:0xf bank_mask:0xf
	v_fmac_f32_dpp v217, v151, v205 row_ror:2 row_mask:0xf bank_mask:0xf
	v_fmac_f32_dpp v218, v152, v206 row_ror:2 row_mask:0xf bank_mask:0xf
	v_fmac_f32_dpp v219, v153, v207 row_ror:2 row_mask:0xf bank_mask:0xf
	v_fmac_f32_dpp v216, v154, v208 row_ror:1 row_mask:0xf bank_mask:0xf
	v_fmac_f32_dpp v217, v155, v209 row_ror:1 row_mask:0xf bank_mask:0xf
	v_fmac_f32_dpp v218, v156, v210 row_ror:1 row_mask:0xf bank_mask:0xf
	v_fmac_f32_dpp v219, v157, v211 row_ror:1 row_mask:0xf bank_mask:0xf
	v_pk_fma_f32 v[160:161], v[134:135], v[212:213], v[216:217]
	v_pk_fma_f32 v[162:163], v[136:137], v[214:215], v[218:219]
	ds_read_b128 v[204:207], v141 offset:16
	ds_read_b128 v[208:211], v141 offset:1040
	ds_read_b128 v[212:215], v141 offset:2064
	ds_read_b128 v[216:219], v141 offset:3088
	ds_read_b128 v[172:175], v159 offset:16
	ds_read_b128 v[176:179], v159 offset:1040
	s_waitcnt lgkmcnt(6)
	v_pk_mul_f32 v[134:135], v[122:123], v[138:139] op_sel_hi:[1,0]
	v_pk_mul_f32 v[136:137], v[124:125], v[138:139] op_sel_hi:[1,0]
	s_and_saveexec_b64 s[0:1], vcc
	s_cbranch_execz .Lmy_u00_1
	v_cvt_pk_bf16_f32 v150, v134, v135
	v_cvt_pk_bf16_f32 v151, v136, v137
	s_nop 0
	global_store_dwordx2 v[144:145], v[150:151], off
;     template <bool SAMPLE> __device__ __forceinline__ void body(const pg8::f32x4 (&acc)[2][2][4][2], const pg8::Unit& u, int wr, int fr, int cl0_, int acol0, LAS float* CW, LAS float* BD, LAS float* RSL) const {
;     ...
;                         const int cl = bj * 128 + cl0 + 4 * n, gcol = bj * DFF + acol0 + cl0 + 4 * n; const f32x4 x = acc[ai][bj][m][n] * rs;
;                         f32x4 s1, s2;
; #pragma unroll
;                         for (int i = 0; i < 4; ++i) { s1[i] = dpp_ror1(x[i]); s2[i] = dpp_ror2(x[i]); }
;                         if (SAMPLE) { const int t = fro & 3; const float* sp = state_conv + (size_t)((row - MP) >> 2) * 2 * UPW + gcol;
;                             const f32x4 S0 = *(const GAS f32x4*)sp, S1 = *(const GAS f32x4*)(sp + UPW);
; #pragma unroll
;                             for (int i = 0; i < 4; ++i) { s1[i] = (t >= 1) ? s1[i] : S1[i]; s2[i] = (t >= 2) ? s2[i] : (t == 1 ? S1[i] : S0[i]); }
;                             if (t >= 2) *(GAS f32x4*)(out + O_CVS + ((size_t)((row - MP) >> 2) * 2 + (t - 2)) * UPW + gcol) = x;
;                         } else if (m > 0) { const f32x4 xp = acc[ai][bj][m > 0 ? m - 1 : 0][n] * RSL[rl - 16];
; #pragma unroll
;                             for (int i = 0; i < 4; ++i) { s1[i] = dpp_ror1(fro == 15 ? xp[i] : x[i]); s2[i] = dpp_ror2(fro >= 14 ? xp[i] : x[i]); }
;                         } else { const int pb = (wr == 1) ? ai * 2 : 1;
;                             const int pr0 = (pb >> 1) * 128 + (pb & 1) * 64 + 62;
;                             const f32x4 b2 = *(const LAS f32x4*)(BD + (pb * 2 + 0) * 256 + cl) * RSL[pr0], b1 = *(const LAS f32x4*)(BD + (pb * 2 + 1) * 256 + cl) * RSL[pr0 + 1];
; #pragma unroll
;                             for (int i = 0; i < 4; ++i) { s1[i] = (fro >= 1) ? s1[i] : b1[i]; s2[i] = (fro >= 2) ? s2[i] : (fro == 1 ? b1[i] : b2[i]); }
;                         }
;                         const f32x4 w0 = *(const LAS f32x4*)(CW + cl), w1 = *(const LAS f32x4*)(CW + 256 + cl), w2 = *(const LAS f32x4*)(CW + 512 + cl), cb = *(const LAS f32x4*)(CW + 768 + cl);
;                         cv2[bj] = cb + s2 * w0 + s1 * w1 + x * w2;
;                         if (!SAMPLE && ai == 0 && m == 0) { if (rl < 2) { v2u w; w.x = cvt_pk_bf16(x[0], x[1]); w.y = cvt_pk_bf16(x[2], x[3]); *(GAS v2u*)(UPF + ((size_t)u.pm * 2 + rl) * UPW + gcol) = w; } }
.Lmy_u00_1:
	s_or_b64 exec, exec, s[0:1]
	v_pk_mul_f32 v[244:245], v[244:245], v[168:169] op_sel_hi:[1,0]
	v_pk_mul_f32 v[246:247], v[246:247], v[168:169] op_sel_hi:[1,0]
	v_pk_mul_f32 v[248:249], v[248:249], v[170:171] op_sel_hi:[1,0]
	v_pk_mul_f32 v[250:251], v[250:251], v[170:171] op_sel_hi:[1,0]
	v_cndmask_b32_e64 v150, v248, v244, s[6:7]
	v_cndmask_b32_e64 v151, v249, v245, s[6:7]
	v_cndmask_b32_e64 v152, v250, v246, s[6:7]
	v_cndmask_b32_e64 v153, v251, v247, s[6:7]
	v_cndmask_b32_e64 v154, v134, v150, s[4:5]
	v_cndmask_b32_e64 v155, v135, v151, s[4:5]
	v_cndmask_b32_e64 v156, v136, v152, s[4:5]
	v_cndmask_b32_e64 v157, v137, v153, s[4:5]
	v_cndmask_b32_e64 v150, v134, v150, s[2:3]
	v_cndmask_b32_e64 v151, v135, v151, s[2:3]
	v_cndmask_b32_e64 v152, v136, v152, s[2:3]
	v_cndmask_b32_e64 v153, v137, v153, s[2:3]
	v_fmac_f32_dpp v240, v150, v228 row_ror:2 row_mask:0xf bank_mask:0xf
	v_fmac_f32_dpp v241, v151, v229 row_ror:2 row_mask:0xf bank_mask:0xf
	v_fmac_f32_dpp v242, v152, v230 row_ror:2 row_mask:0xf bank_mask:0xf
	v_fmac_f32_dpp v243, v153, v231 row_ror:2 row_mask:0xf bank_mask:0xf
	v_fmac_f32_dpp v240, v154, v232 row_ror:1 row_mask:0xf bank_mask:0xf
	v_fmac_f32_dpp v241, v155, v233 row_ror:1 row_mask:0xf bank_mask:0xf
	v_fmac_f32_dpp v242, v156, v234 row_ror:1 row_mask:0xf bank_mask:0xf
	v_fmac_f32_dpp v243, v157, v235 row_ror:1 row_mask:0xf bank_mask:0xf
	v_pk_fma_f32 v[164:165], v[134:135], v[236:237], v[240:241]
	v_pk_fma_f32 v[166:167], v[136:137], v[238:239], v[242:243]
	ds_read_b128 v[228:231], v141 offset:528
	ds_read_b128 v[232:235], v141 offset:1552
	ds_read_b128 v[236:239], v141 offset:2576
	ds_read_b128 v[240:243], v141 offset:3600
	ds_read_b128 v[244:247], v159 offset:528
	ds_read_b128 v[248:251], v159 offset:1552
	v_pk_mul_f32 v[134:135], v[160:161], v[160:161]
	v_pk_mul_f32 v[136:137], v[162:163], v[162:163]
	v_pk_fma_f32 v[134:135], v[134:135], s[54:55], 1.0 op_sel_hi:[1,0,0]
	v_pk_mul_f32 v[150:151], v[160:161], s[56:57] op_sel_hi:[1,0]
	v_pk_fma_f32 v[136:137], v[136:137], s[54:55], 1.0 op_sel_hi:[1,0,0]
	v_pk_mul_f32 v[152:153], v[162:163], s[56:57] op_sel_hi:[1,0]
	v_pk_mul_f32 v[134:135], v[150:151], v[134:135]
	v_pk_mul_f32 v[136:137], v[152:153], v[136:137]
	v_pk_mul_f32 v[134:135], v[134:135], s[58:59] op_sel_hi:[1,0]
	v_pk_mul_f32 v[136:137], v[136:137], s[58:59] op_sel_hi:[1,0]
	v_exp_f32_e32 v134, v134
	v_exp_f32_e32 v135, v135
	v_exp_f32_e32 v136, v136
	v_exp_f32_e32 v137, v137
	v_pk_add_f32 v[134:135], v[134:135], 1.0 op_sel_hi:[1,0]
	s_nop 0
	v_pk_add_f32 v[136:137], v[136:137], 1.0 op_sel_hi:[1,0]
	v_rcp_f32_e32 v134, v134
	v_rcp_f32_e32 v135, v135
	v_rcp_f32_e32 v136, v136
	v_rcp_f32_e32 v137, v137
	v_pk_mul_f32 v[134:135], v[160:161], v[134:135]
	v_pk_mul_f32 v[136:137], v[162:163], v[136:137]
	v_pk_mul_f32 v[134:135], v[164:165], v[134:135]
	v_pk_mul_f32 v[136:137], v[166:167], v[136:137]
	s_nop 0
	v_cvt_pk_bf16_f32 v130, v134, v135
	v_cvt_pk_bf16_f32 v131, v136, v137
	s_waitcnt lgkmcnt(6)
	v_pk_mul_f32 v[134:135], v[118:119], v[138:139] op_sel_hi:[1,0]
	v_pk_mul_f32 v[136:137], v[120:121], v[138:139] op_sel_hi:[1,0]
	s_and_saveexec_b64 s[0:1], vcc
	s_cbranch_execz .Lmy_u00_2
	v_cvt_pk_bf16_f32 v150, v134, v135
	v_cvt_pk_bf16_f32 v151, v136, v137
	s_nop 0
	global_store_dwordx2 v[142:143], v[150:151], off offset:8
;     template <bool SAMPLE> __device__ __forceinline__ void body(const pg8::f32x4 (&acc)[2][2][4][2], const pg8::Unit& u, int wr, int fr, int cl0_, int acol0, LAS float* CW, LAS float* BD, LAS float* RSL) const {
;     ...
;                         const int cl = bj * 128 + cl0 + 4 * n, gcol = bj * DFF + acol0 + cl0 + 4 * n; const f32x4 x = acc[ai][bj][m][n] * rs;
;                         f32x4 s1, s2;
; #pragma unroll
;                         for (int i = 0; i < 4; ++i) { s1[i] = dpp_ror1(x[i]); s2[i] = dpp_ror2(x[i]); }
;                         if (SAMPLE) { const int t = fro & 3; const float* sp = state_conv + (size_t)((row - MP) >> 2) * 2 * UPW + gcol;
;                             const f32x4 S0 = *(const GAS f32x4*)sp, S1 = *(const GAS f32x4*)(sp + UPW);
; #pragma unroll
;                             for (int i = 0; i < 4; ++i) { s1[i] = (t >= 1) ? s1[i] : S1[i]; s2[i] = (t >= 2) ? s2[i] : (t == 1 ? S1[i] : S0[i]); }
;                             if (t >= 2) *(GAS f32x4*)(out + O_CVS + ((size_t)((row - MP) >> 2) * 2 + (t - 2)) * UPW + gcol) = x;
;                         } else if (m > 0) { const f32x4 xp = acc[ai][bj][m > 0 ? m - 1 : 0][n] * RSL[rl - 16];
; #pragma unroll
;                             for (int i = 0; i < 4; ++i) { s1[i] = dpp_ror1(fro == 15 ? xp[i] : x[i]); s2[i] = dpp_ror2(fro >= 14 ? xp[i] : x[i]); }
;                         } else { const int pb = (wr == 1) ? ai * 2 : 1;
;                             const int pr0 = (pb >> 1) * 128 + (pb & 1) * 64 + 62;
;                             const f32x4 b2 = *(const LAS f32x4*)(BD + (pb * 2 + 0) * 256 + cl) * RSL[pr0], b1 = *(const LAS f32x4*)(BD + (pb * 2 + 1) * 256 + cl) * RSL[pr0 + 1];
; #pragma unroll
;                             for (int i = 0; i < 4; ++i) { s1[i] = (fro >= 1) ? s1[i] : b1[i]; s2[i] = (fro >= 2) ? s2[i] : (fro == 1 ? b1[i] : b2[i]); }
;                         }
;                         const f32x4 w0 = *(const LAS f32x4*)(CW + cl), w1 = *(const LAS f32x4*)(CW + 256 + cl), w2 = *(const LAS f32x4*)(CW + 512 + cl), cb = *(const LAS f32x4*)(CW + 768 + cl);
;                         cv2[bj] = cb + s2 * w0 + s1 * w1 + x * w2;
;                         if (!SAMPLE && ai == 0 && m == 0) { if (rl < 2) { v2u w; w.x = cvt_pk_bf16(x[0], x[1]); w.y = cvt_pk_bf16(x[2], x[3]); *(GAS v2u*)(UPF + ((size_t)u.pm * 2 + rl) * UPW + gcol) = w; } }
.Lmy_u00_2:
	s_or_b64 exec, exec, s[0:1]
	v_pk_mul_f32 v[172:173], v[172:173], v[168:169] op_sel_hi:[1,0]
	v_pk_mul_f32 v[174:175], v[174:175], v[168:169] op_sel_hi:[1,0]
	v_pk_mul_f32 v[176:177], v[176:177], v[170:171] op_sel_hi:[1,0]
	v_pk_mul_f32 v[178:179], v[178:179], v[170:171] op_sel_hi:[1,0]
	v_cndmask_b32_e64 v150, v176, v172, s[6:7]
	v_cndmask_b32_e64 v151, v177, v173, s[6:7]
	v_cndmask_b32_e64 v152, v178, v174, s[6:7]
	v_cndmask_b32_e64 v153, v179, v175, s[6:7]
	v_cndmask_b32_e64 v154, v134, v150, s[4:5]
	v_cndmask_b32_e64 v155, v135, v151, s[4:5]
	v_cndmask_b32_e64 v156, v136, v152, s[4:5]
	v_cndmask_b32_e64 v157, v137, v153, s[4:5]
	v_cndmask_b32_e64 v150, v134, v150, s[2:3]
	v_cndmask_b32_e64 v151, v135, v151, s[2:3]
	v_cndmask_b32_e64 v152, v136, v152, s[2:3]
	v_cndmask_b32_e64 v153, v137, v153, s[2:3]
	v_fmac_f32_dpp v216, v150, v204 row_ror:2 row_mask:0xf bank_mask:0xf
	v_fmac_f32_dpp v217, v151, v205 row_ror:2 row_mask:0xf bank_mask:0xf
	v_fmac_f32_dpp v218, v152, v206 row_ror:2 row_mask:0xf bank_mask:0xf
	v_fmac_f32_dpp v219, v153, v207 row_ror:2 row_mask:0xf bank_mask:0xf
	v_fmac_f32_dpp v216, v154, v208 row_ror:1 row_mask:0xf bank_mask:0xf
	v_fmac_f32_dpp v217, v155, v209 row_ror:1 row_mask:0xf bank_mask:0xf
	v_fmac_f32_dpp v218, v156, v210 row_ror:1 row_mask:0xf bank_mask:0xf
	v_fmac_f32_dpp v219, v157, v211 row_ror:1 row_mask:0xf bank_mask:0xf
	v_pk_fma_f32 v[160:161], v[134:135], v[212:213], v[216:217]
	v_pk_fma_f32 v[162:163], v[136:137], v[214:215], v[218:219]
	s_waitcnt lgkmcnt(0)
	v_pk_mul_f32 v[134:135], v[114:115], v[138:139] op_sel_hi:[1,0]
	v_pk_mul_f32 v[136:137], v[116:117], v[138:139] op_sel_hi:[1,0]
	s_and_saveexec_b64 s[0:1], vcc
	s_cbranch_execz .Lmy_u00_3
	v_cvt_pk_bf16_f32 v150, v134, v135
	v_cvt_pk_bf16_f32 v151, v136, v137
	s_nop 0
	global_store_dwordx2 v[144:145], v[150:151], off offset:8
.Lmy_u00_3:
	s_or_b64 exec, exec, s[0:1]
	v_pk_mul_f32 v[244:245], v[244:245], v[168:169] op_sel_hi:[1,0]
	v_pk_mul_f32 v[246:247], v[246:247], v[168:169] op_sel_hi:[1,0]
	v_pk_mul_f32 v[248:249], v[248:249], v[170:171] op_sel_hi:[1,0]
	v_pk_mul_f32 v[250:251], v[250:251], v[170:171] op_sel_hi:[1,0]
	v_cndmask_b32_e64 v150, v248, v244, s[6:7]
	v_cndmask_b32_e64 v151, v249, v245, s[6:7]
	v_cndmask_b32_e64 v152, v250, v246, s[6:7]
	v_cndmask_b32_e64 v153, v251, v247, s[6:7]
	v_cndmask_b32_e64 v154, v134, v150, s[4:5]
	v_cndmask_b32_e64 v155, v135, v151, s[4:5]
	v_cndmask_b32_e64 v156, v136, v152, s[4:5]
	v_cndmask_b32_e64 v157, v137, v153, s[4:5]
	v_cndmask_b32_e64 v150, v134, v150, s[2:3]
	v_cndmask_b32_e64 v151, v135, v151, s[2:3]
	v_cndmask_b32_e64 v152, v136, v152, s[2:3]
	v_cndmask_b32_e64 v153, v137, v153, s[2:3]
	v_fmac_f32_dpp v240, v150, v228 row_ror:2 row_mask:0xf bank_mask:0xf
	v_fmac_f32_dpp v241, v151, v229 row_ror:2 row_mask:0xf bank_mask:0xf
	v_fmac_f32_dpp v242, v152, v230 row_ror:2 row_mask:0xf bank_mask:0xf
	v_fmac_f32_dpp v243, v153, v231 row_ror:2 row_mask:0xf bank_mask:0xf
	v_fmac_f32_dpp v240, v154, v232 row_ror:1 row_mask:0xf bank_mask:0xf
	v_fmac_f32_dpp v241, v155, v233 row_ror:1 row_mask:0xf bank_mask:0xf
	v_fmac_f32_dpp v242, v156, v234 row_ror:1 row_mask:0xf bank_mask:0xf
	v_fmac_f32_dpp v243, v157, v235 row_ror:1 row_mask:0xf bank_mask:0xf
	v_pk_fma_f32 v[164:165], v[134:135], v[236:237], v[240:241]
	v_pk_fma_f32 v[166:167], v[136:137], v[238:239], v[242:243]
	v_pk_mul_f32 v[134:135], v[160:161], v[160:161]
	v_pk_mul_f32 v[136:137], v[162:163], v[162:163]
	v_pk_fma_f32 v[134:135], v[134:135], s[54:55], 1.0 op_sel_hi:[1,0,0]
	v_pk_mul_f32 v[150:151], v[160:161], s[56:57] op_sel_hi:[1,0]
	v_pk_fma_f32 v[136:137], v[136:137], s[54:55], 1.0 op_sel_hi:[1,0,0]
	v_pk_mul_f32 v[152:153], v[162:163], s[56:57] op_sel_hi:[1,0]
	v_pk_mul_f32 v[134:135], v[150:151], v[134:135]
	v_pk_mul_f32 v[136:137], v[152:153], v[136:137]
	v_pk_mul_f32 v[134:135], v[134:135], s[58:59] op_sel_hi:[1,0]
	v_pk_mul_f32 v[136:137], v[136:137], s[58:59] op_sel_hi:[1,0]
	v_exp_f32_e32 v134, v134
	v_exp_f32_e32 v135, v135
	v_exp_f32_e32 v136, v136
	v_exp_f32_e32 v137, v137
	v_pk_add_f32 v[134:135], v[134:135], 1.0 op_sel_hi:[1,0]
	s_nop 0
	v_pk_add_f32 v[136:137], v[136:137], 1.0 op_sel_hi:[1,0]
	v_rcp_f32_e32 v134, v134
	v_rcp_f32_e32 v135, v135
	v_rcp_f32_e32 v136, v136
	v_rcp_f32_e32 v137, v137
	v_pk_mul_f32 v[134:135], v[160:161], v[134:135]
	v_pk_mul_f32 v[136:137], v[162:163], v[136:137]
	v_pk_mul_f32 v[134:135], v[164:165], v[134:135]
	v_pk_mul_f32 v[136:137], v[166:167], v[136:137]
	s_nop 0
	v_cvt_pk_bf16_f32 v132, v134, v135
	v_cvt_pk_bf16_f32 v133, v136, v137
	v_cmp_lt_i32_e32 vcc, 1, v158
	s_and_saveexec_b64 s[0:1], vcc
	s_cbranch_execz .LBB0_2606
	v_add_u32_e32 v136, s16, v158
	v_mov_b64_e32 v[134:135], s[50:51]
	v_mad_i64_i32 v[134:135], s[2:3], v136, s82, v[134:135]
	v_ashrrev_i32_e32 v141, 31, v140
	v_lshl_add_u64 v[134:135], s[36:37], 1, v[134:135]
	v_lshl_add_u64 v[134:135], v[140:141], 1, v[134:135]
	global_store_dwordx4 v[134:135], v[130:133], off

;     template <bool SAMPLE> __device__ __forceinline__ void body(const pg8::f32x4 (&acc)[2][2][4][2], const pg8::Unit& u, int wr, int fr, int cl0_, int acol0, LAS float* CW, LAS float* BD, LAS float* RSL) const {
;     ...
;                         const int cl = bj * 128 + cl0 + 4 * n, gcol = bj * DFF + acol0 + cl0 + 4 * n; const f32x4 x = acc[ai][bj][m][n] * rs;
;                         f32x4 s1, s2;
; #pragma unroll
;                         for (int i = 0; i < 4; ++i) { s1[i] = dpp_ror1(x[i]); s2[i] = dpp_ror2(x[i]); }
;                         if (SAMPLE) { const int t = fro & 3; const float* sp = state_conv + (size_t)((row - MP) >> 2) * 2 * UPW + gcol;
;                             const f32x4 S0 = *(const GAS f32x4*)sp, S1 = *(const GAS f32x4*)(sp + UPW);
; #pragma unroll
;                             for (int i = 0; i < 4; ++i) { s1[i] = (t >= 1) ? s1[i] : S1[i]; s2[i] = (t >= 2) ? s2[i] : (t == 1 ? S1[i] : S0[i]); }
;                             if (t >= 2) *(GAS f32x4*)(out + O_CVS + ((size_t)((row - MP) >> 2) * 2 + (t - 2)) * UPW + gcol) = x;
;                         } else if (m > 0) { const f32x4 xp = acc[ai][bj][m > 0 ? m - 1 : 0][n] * RSL[rl - 16];
; #pragma unroll
;                             for (int i = 0; i < 4; ++i) { s1[i] = dpp_ror1(fro == 15 ? xp[i] : x[i]); s2[i] = dpp_ror2(fro >= 14 ? xp[i] : x[i]); }
;                         } else { const int pb = (wr == 1) ? ai * 2 : 1;
;                             const int pr0 = (pb >> 1) * 128 + (pb & 1) * 64 + 62;
;                             const f32x4 b2 = *(const LAS f32x4*)(BD + (pb * 2 + 0) * 256 + cl) * RSL[pr0], b1 = *(const LAS f32x4*)(BD + (pb * 2 + 1) * 256 + cl) * RSL[pr0 + 1];
; #pragma unroll
;                             for (int i = 0; i < 4; ++i) { s1[i] = (fro >= 1) ? s1[i] : b1[i]; s2[i] = (fro >= 2) ? s2[i] : (fro == 1 ? b1[i] : b2[i]); }
;                         }
;                         const f32x4 w0 = *(const LAS f32x4*)(CW + cl), w1 = *(const LAS f32x4*)(CW + 256 + cl), w2 = *(const LAS f32x4*)(CW + 512 + cl), cb = *(const LAS f32x4*)(CW + 768 + cl);
;                         cv2[bj] = cb + s2 * w0 + s1 * w1 + x * w2;
;                         if (!SAMPLE && ai == 0 && m == 0) { if (rl < 2) { v2u w; w.x = cvt_pk_bf16(x[0], x[1]); w.y = cvt_pk_bf16(x[2], x[3]); *(GAS v2u*)(UPF + ((size_t)u.pm * 2 + rl) * UPW + gcol) = w; } }
.LBB0_2612:
	s_or_b64 exec, exec, s[0:1]
	v_readlane_b32 s0, v255, 38
	v_readlane_b32 s1, v255, 34
	v_mov_b32_e32 v140, v198
	v_lshl_add_u32 v141, v198, 2, 0
	v_cmp_eq_u32_e64 s[4:5], 15, v199
	v_cmp_lt_i32_e64 s[2:3], 13, v199
	v_cmp_eq_u32_e64 s[6:7], 14, v199
	v_add_u32_e32 v158, s86, v199
	v_add_u32_e32 v159, s0, v141
	v_add_u32_e32 v141, 0x20000, v141
	s_add_i32 s1, s17, s1
	v_lshl_add_u32 v138, v158, 2, s17
	v_mov_b32_e32 v168, s1
	ds_read_b32 v138, v138
	ds_read_b32 v170, v168 offset:252
	ds_read_b32 v168, v168 offset:248
	ds_read_b128 v[204:207], v141
	ds_read_b128 v[208:211], v141 offset:1024
	ds_read_b128 v[212:215], v141 offset:2048
	ds_read_b128 v[216:219], v141 offset:3072
	ds_read_b128 v[172:175], v159
	ds_read_b128 v[176:179], v159 offset:1024
	ds_read_b128 v[228:231], v141 offset:512
	ds_read_b128 v[232:235], v141 offset:1536
	ds_read_b128 v[236:239], v141 offset:2560
	ds_read_b128 v[240:243], v141 offset:3584
	ds_read_b128 v[244:247], v159 offset:512
	ds_read_b128 v[248:251], v159 offset:1536
	v_cmp_lt_i32_e32 vcc, 1, v158
	s_waitcnt lgkmcnt(6)
	v_pk_mul_f32 v[134:135], v[62:63], v[138:139] op_sel_hi:[1,0]
	v_pk_mul_f32 v[136:137], v[64:65], v[138:139] op_sel_hi:[1,0]
	v_pk_mul_f32 v[172:173], v[172:173], v[168:169] op_sel_hi:[1,0]
	v_pk_mul_f32 v[174:175], v[174:175], v[168:169] op_sel_hi:[1,0]
	v_pk_mul_f32 v[176:177], v[176:177], v[170:171] op_sel_hi:[1,0]
	v_pk_mul_f32 v[178:179], v[178:179], v[170:171] op_sel_hi:[1,0]
	v_cndmask_b32_e64 v150, v176, v172, s[6:7]
	v_cndmask_b32_e64 v151, v177, v173, s[6:7]
	v_cndmask_b32_e64 v152, v178, v174, s[6:7]
	v_cndmask_b32_e64 v153, v179, v175, s[6:7]
	v_cndmask_b32_e64 v154, v134, v150, s[4:5]
	v_cndmask_b32_e64 v155, v135, v151, s[4:5]
	v_cndmask_b32_e64 v156, v136, v152, s[4:5]
	v_cndmask_b32_e64 v157, v137, v153, s[4:5]
	v_cndmask_b32_e64 v150, v134, v150, s[2:3]
	v_cndmask_b32_e64 v151, v135, v151, s[2:3]
	v_cndmask_b32_e64 v152, v136, v152, s[2:3]
	v_cndmask_b32_e64 v153, v137, v153, s[2:3]
	v_fmac_f32_dpp v216, v150, v204 row_ror:2 row_mask:0xf bank_mask:0xf
	v_fmac_f32_dpp v217, v151, v205 row_ror:2 row_mask:0xf bank_mask:0xf
	v_fmac_f32_dpp v218, v152, v206 row_ror:2 row_mask:0xf bank_mask:0xf
	v_fmac_f32_dpp v219, v153, v207 row_ror:2 row_mask:0xf bank_mask:0xf
	v_fmac_f32_dpp v216, v154, v208 row_ror:1 row_mask:0xf bank_mask:0xf
	v_fmac_f32_dpp v217, v155, v209 row_ror:1 row_mask:0xf bank_mask:0xf
	v_fmac_f32_dpp v218, v156, v210 row_ror:1 row_mask:0xf bank_mask:0xf
	v_fmac_f32_dpp v219, v157, v211 row_ror:1 row_mask:0xf bank_mask:0xf
	v_pk_fma_f32 v[160:161], v[134:135], v[212:213], v[216:217]
	v_pk_fma_f32 v[162:163], v[136:137], v[214:215], v[218:219]
	ds_read_b128 v[204:207], v141 offset:16
	ds_read_b128 v[208:211], v141 offset:1040
	ds_read_b128 v[212:215], v141 offset:2064
	ds_read_b128 v[216:219], v141 offset:3088
	ds_read_b128 v[172:175], v159 offset:16
	ds_read_b128 v[176:179], v159 offset:1040
	s_waitcnt lgkmcnt(6)
	v_pk_mul_f32 v[134:135], v[58:59], v[138:139] op_sel_hi:[1,0]
	v_pk_mul_f32 v[136:137], v[60:61], v[138:139] op_sel_hi:[1,0]
	v_pk_mul_f32 v[244:245], v[244:245], v[168:169] op_sel_hi:[1,0]
	v_pk_mul_f32 v[246:247], v[246:247], v[168:169] op_sel_hi:[1,0]
	v_pk_mul_f32 v[248:249], v[248:249], v[170:171] op_sel_hi:[1,0]
	v_pk_mul_f32 v[250:251], v[250:251], v[170:171] op_sel_hi:[1,0]
	v_cndmask_b32_e64 v150, v248, v244, s[6:7]
	v_cndmask_b32_e64 v151, v249, v245, s[6:7]
	v_cndmask_b32_e64 v152, v250, v246, s[6:7]
	v_cndmask_b32_e64 v153, v251, v247, s[6:7]
	v_cndmask_b32_e64 v154, v134, v150, s[4:5]
	v_cndmask_b32_e64 v155, v135, v151, s[4:5]
	v_cndmask_b32_e64 v156, v136, v152, s[4:5]
	v_cndmask_b32_e64 v157, v137, v153, s[4:5]
	v_cndmask_b32_e64 v150, v134, v150, s[2:3]
	v_cndmask_b32_e64 v151, v135, v151, s[2:3]
	v_cndmask_b32_e64 v152, v136, v152, s[2:3]
	v_cndmask_b32_e64 v153, v137, v153, s[2:3]
	v_fmac_f32_dpp v240, v150, v228 row_ror:2 row_mask:0xf bank_mask:0xf
	v_fmac_f32_dpp v241, v151, v229 row_ror:2 row_mask:0xf bank_mask:0xf
	v_fmac_f32_dpp v242, v152, v230 row_ror:2 row_mask:0xf bank_mask:0xf
	v_fmac_f32_dpp v243, v153, v231 row_ror:2 row_mask:0xf bank_mask:0xf
	v_fmac_f32_dpp v240, v154, v232 row_ror:1 row_mask:0xf bank_mask:0xf
	v_fmac_f32_dpp v241, v155, v233 row_ror:1 row_mask:0xf bank_mask:0xf
	v_fmac_f32_dpp v242, v156, v234 row_ror:1 row_mask:0xf bank_mask:0xf
	v_fmac_f32_dpp v243, v157, v235 row_ror:1 row_mask:0xf bank_mask:0xf
	v_pk_fma_f32 v[164:165], v[134:135], v[236:237], v[240:241]
	v_pk_fma_f32 v[166:167], v[136:137], v[238:239], v[242:243]
	ds_read_b128 v[228:231], v141 offset:528
	ds_read_b128 v[232:235], v141 offset:1552
	ds_read_b128 v[236:239], v141 offset:2576
	ds_read_b128 v[240:243], v141 offset:3600
	ds_read_b128 v[244:247], v159 offset:528
	ds_read_b128 v[248:251], v159 offset:1552
	v_pk_mul_f32 v[134:135], v[160:161], v[160:161]
	v_pk_mul_f32 v[136:137], v[162:163], v[162:163]
	v_pk_fma_f32 v[134:135], v[134:135], s[54:55], 1.0 op_sel_hi:[1,0,0]
	v_pk_mul_f32 v[150:151], v[160:161], s[56:57] op_sel_hi:[1,0]
	v_pk_fma_f32 v[136:137], v[136:137], s[54:55], 1.0 op_sel_hi:[1,0,0]
	v_pk_mul_f32 v[152:153], v[162:163], s[56:57] op_sel_hi:[1,0]
	v_pk_mul_f32 v[134:135], v[150:151], v[134:135]
	v_pk_mul_f32 v[136:137], v[152:153], v[136:137]
	v_pk_mul_f32 v[134:135], v[134:135], s[58:59] op_sel_hi:[1,0]
	v_pk_mul_f32 v[136:137], v[136:137], s[58:59] op_sel_hi:[1,0]
	v_exp_f32_e32 v134, v134
	v_exp_f32_e32 v135, v135
	v_exp_f32_e32 v136, v136
	v_exp_f32_e32 v137, v137
	v_pk_add_f32 v[134:135], v[134:135], 1.0 op_sel_hi:[1,0]
	s_nop 0
	v_pk_add_f32 v[136:137], v[136:137], 1.0 op_sel_hi:[1,0]
	v_rcp_f32_e32 v134, v134
	v_rcp_f32_e32 v135, v135
	v_rcp_f32_e32 v136, v136
	v_rcp_f32_e32 v137, v137
	v_pk_mul_f32 v[134:135], v[160:161], v[134:135]
	v_pk_mul_f32 v[136:137], v[162:163], v[136:137]
	v_pk_mul_f32 v[134:135], v[164:165], v[134:135]
	v_pk_mul_f32 v[136:137], v[166:167], v[136:137]
	s_nop 0
	v_cvt_pk_bf16_f32 v130, v134, v135
	v_cvt_pk_bf16_f32 v131, v136, v137
	s_waitcnt lgkmcnt(6)
;     template <bool SAMPLE> __device__ __forceinline__ void body(const pg8::f32x4 (&acc)[2][2][4][2], const pg8::Unit& u, int wr, int fr, int cl0_, int acol0, LAS float* CW, LAS float* BD, LAS float* RSL) const {
;     ...
;                         const int cl = bj * 128 + cl0 + 4 * n, gcol = bj * DFF + acol0 + cl0 + 4 * n; const f32x4 x = acc[ai][bj][m][n] * rs;
;                         f32x4 s1, s2;
; #pragma unroll
;                         for (int i = 0; i < 4; ++i) { s1[i] = dpp_ror1(x[i]); s2[i] = dpp_ror2(x[i]); }
;                         if (SAMPLE) { const int t = fro & 3; const float* sp = state_conv + (size_t)((row - MP) >> 2) * 2 * UPW + gcol;
;                             const f32x4 S0 = *(const GAS f32x4*)sp, S1 = *(const GAS f32x4*)(sp + UPW);
; #pragma unroll
;                             for (int i = 0; i < 4; ++i) { s1[i] = (t >= 1) ? s1[i] : S1[i]; s2[i] = (t >= 2) ? s2[i] : (t == 1 ? S1[i] : S0[i]); }
;                             if (t >= 2) *(GAS f32x4*)(out + O_CVS + ((size_t)((row - MP) >> 2) * 2 + (t - 2)) * UPW + gcol) = x;
;                         } else if (m > 0) { const f32x4 xp = acc[ai][bj][m > 0 ? m - 1 : 0][n] * RSL[rl - 16];
; #pragma unroll
;                             for (int i = 0; i < 4; ++i) { s1[i] = dpp_ror1(fro == 15 ? xp[i] : x[i]); s2[i] = dpp_ror2(fro >= 14 ? xp[i] : x[i]); }
;                         } else { const int pb = (wr == 1) ? ai * 2 : 1;
;                             const int pr0 = (pb >> 1) * 128 + (pb & 1) * 64 + 62;
;                             const f32x4 b2 = *(const LAS f32x4*)(BD + (pb * 2 + 0) * 256 + cl) * RSL[pr0], b1 = *(const LAS f32x4*)(BD + (pb * 2 + 1) * 256 + cl) * RSL[pr0 + 1];
; #pragma unroll
;                             for (int i = 0; i < 4; ++i) { s1[i] = (fro >= 1) ? s1[i] : b1[i]; s2[i] = (fro >= 2) ? s2[i] : (fro == 1 ? b1[i] : b2[i]); }
;                         }
;                         const f32x4 w0 = *(const LAS f32x4*)(CW + cl), w1 = *(const LAS f32x4*)(CW + 256 + cl), w2 = *(const LAS f32x4*)(CW + 512 + cl), cb = *(const LAS f32x4*)(CW + 768 + cl);
;                         cv2[bj] = cb + s2 * w0 + s1 * w1 + x * w2;
;                         if (!SAMPLE && ai == 0 && m == 0) { if (rl < 2) { v2u w; w.x = cvt_pk_bf16(x[0], x[1]); w.y = cvt_pk_bf16(x[2], x[3]); *(GAS v2u*)(UPF + ((size_t)u.pm * 2 + rl) * UPW + gcol) = w; } }
	v_pk_mul_f32 v[134:135], v[54:55], v[138:139] op_sel_hi:[1,0]
	v_pk_mul_f32 v[136:137], v[56:57], v[138:139] op_sel_hi:[1,0]
	v_pk_mul_f32 v[172:173], v[172:173], v[168:169] op_sel_hi:[1,0]
	v_pk_mul_f32 v[174:175], v[174:175], v[168:169] op_sel_hi:[1,0]
	v_pk_mul_f32 v[176:177], v[176:177], v[170:171] op_sel_hi:[1,0]
	v_pk_mul_f32 v[178:179], v[178:179], v[170:171] op_sel_hi:[1,0]
	v_cndmask_b32_e64 v150, v176, v172, s[6:7]
	v_cndmask_b32_e64 v151, v177, v173, s[6:7]
	v_cndmask_b32_e64 v152, v178, v174, s[6:7]
	v_cndmask_b32_e64 v153, v179, v175, s[6:7]
	v_cndmask_b32_e64 v154, v134, v150, s[4:5]
	v_cndmask_b32_e64 v155, v135, v151, s[4:5]
	v_cndmask_b32_e64 v156, v136, v152, s[4:5]
	v_cndmask_b32_e64 v157, v137, v153, s[4:5]
	v_cndmask_b32_e64 v150, v134, v150, s[2:3]
	v_cndmask_b32_e64 v151, v135, v151, s[2:3]
	v_cndmask_b32_e64 v152, v136, v152, s[2:3]
	v_cndmask_b32_e64 v153, v137, v153, s[2:3]
	v_fmac_f32_dpp v216, v150, v204 row_ror:2 row_mask:0xf bank_mask:0xf
	v_fmac_f32_dpp v217, v151, v205 row_ror:2 row_mask:0xf bank_mask:0xf
	v_fmac_f32_dpp v218, v152, v206 row_ror:2 row_mask:0xf bank_mask:0xf
	v_fmac_f32_dpp v219, v153, v207 row_ror:2 row_mask:0xf bank_mask:0xf
	v_fmac_f32_dpp v216, v154, v208 row_ror:1 row_mask:0xf bank_mask:0xf
	v_fmac_f32_dpp v217, v155, v209 row_ror:1 row_mask:0xf bank_mask:0xf
	v_fmac_f32_dpp v218, v156, v210 row_ror:1 row_mask:0xf bank_mask:0xf
	v_fmac_f32_dpp v219, v157, v211 row_ror:1 row_mask:0xf bank_mask:0xf
	v_pk_fma_f32 v[160:161], v[134:135], v[212:213], v[216:217]
	v_pk_fma_f32 v[162:163], v[136:137], v[214:215], v[218:219]
	s_waitcnt lgkmcnt(0)
	v_pk_mul_f32 v[134:135], v[50:51], v[138:139] op_sel_hi:[1,0]
	v_pk_mul_f32 v[136:137], v[52:53], v[138:139] op_sel_hi:[1,0]
	v_pk_mul_f32 v[244:245], v[244:245], v[168:169] op_sel_hi:[1,0]
	v_pk_mul_f32 v[246:247], v[246:247], v[168:169] op_sel_hi:[1,0]
	v_pk_mul_f32 v[248:249], v[248:249], v[170:171] op_sel_hi:[1,0]
	v_pk_mul_f32 v[250:251], v[250:251], v[170:171] op_sel_hi:[1,0]
	v_cndmask_b32_e64 v150, v248, v244, s[6:7]
	v_cndmask_b32_e64 v151, v249, v245, s[6:7]
	v_cndmask_b32_e64 v152, v250, v246, s[6:7]
	v_cndmask_b32_e64 v153, v251, v247, s[6:7]
	v_cndmask_b32_e64 v154, v134, v150, s[4:5]
	v_cndmask_b32_e64 v155, v135, v151, s[4:5]
	v_cndmask_b32_e64 v156, v136, v152, s[4:5]
	v_cndmask_b32_e64 v157, v137, v153, s[4:5]
	v_cndmask_b32_e64 v150, v134, v150, s[2:3]
	v_cndmask_b32_e64 v151, v135, v151, s[2:3]
	v_cndmask_b32_e64 v152, v136, v152, s[2:3]
	v_cndmask_b32_e64 v153, v137, v153, s[2:3]
	v_fmac_f32_dpp v240, v150, v228 row_ror:2 row_mask:0xf bank_mask:0xf
	v_fmac_f32_dpp v241, v151, v229 row_ror:2 row_mask:0xf bank_mask:0xf
	v_fmac_f32_dpp v242, v152, v230 row_ror:2 row_mask:0xf bank_mask:0xf
	v_fmac_f32_dpp v243, v153, v231 row_ror:2 row_mask:0xf bank_mask:0xf
	v_fmac_f32_dpp v240, v154, v232 row_ror:1 row_mask:0xf bank_mask:0xf
	v_fmac_f32_dpp v241, v155, v233 row_ror:1 row_mask:0xf bank_mask:0xf
	v_fmac_f32_dpp v242, v156, v234 row_ror:1 row_mask:0xf bank_mask:0xf
	v_fmac_f32_dpp v243, v157, v235 row_ror:1 row_mask:0xf bank_mask:0xf
	v_pk_fma_f32 v[164:165], v[134:135], v[236:237], v[240:241]
	v_pk_fma_f32 v[166:167], v[136:137], v[238:239], v[242:243]
	v_pk_mul_f32 v[134:135], v[160:161], v[160:161]
	v_pk_mul_f32 v[136:137], v[162:163], v[162:163]
	v_pk_fma_f32 v[134:135], v[134:135], s[54:55], 1.0 op_sel_hi:[1,0,0]
	v_pk_mul_f32 v[150:151], v[160:161], s[56:57] op_sel_hi:[1,0]
	v_pk_fma_f32 v[136:137], v[136:137], s[54:55], 1.0 op_sel_hi:[1,0,0]
	v_pk_mul_f32 v[152:153], v[162:163], s[56:57] op_sel_hi:[1,0]
	v_pk_mul_f32 v[134:135], v[150:151], v[134:135]
	v_pk_mul_f32 v[136:137], v[152:153], v[136:137]
	v_pk_mul_f32 v[134:135], v[134:135], s[58:59] op_sel_hi:[1,0]
	v_pk_mul_f32 v[136:137], v[136:137], s[58:59] op_sel_hi:[1,0]
	v_exp_f32_e32 v134, v134
	v_exp_f32_e32 v135, v135
	v_exp_f32_e32 v136, v136
	v_exp_f32_e32 v137, v137
	v_pk_add_f32 v[134:135], v[134:135], 1.0 op_sel_hi:[1,0]
	s_nop 0
	v_pk_add_f32 v[136:137], v[136:137], 1.0 op_sel_hi:[1,0]
	v_rcp_f32_e32 v134, v134
	v_rcp_f32_e32 v135, v135
	v_rcp_f32_e32 v136, v136
	v_rcp_f32_e32 v137, v137
	v_pk_mul_f32 v[134:135], v[160:161], v[134:135]
	v_pk_mul_f32 v[136:137], v[162:163], v[136:137]
	v_pk_mul_f32 v[134:135], v[164:165], v[134:135]
	v_pk_mul_f32 v[136:137], v[166:167], v[136:137]
	s_nop 0
	v_cvt_pk_bf16_f32 v132, v134, v135
	v_cvt_pk_bf16_f32 v133, v136, v137
	s_and_saveexec_b64 s[0:1], vcc
	s_cbranch_execz .LBB0_2614
	v_add_u32_e32 v136, s16, v158
	v_mov_b64_e32 v[134:135], s[50:51]
	v_mad_i64_i32 v[134:135], s[2:3], v136, s82, v[134:135]
	v_ashrrev_i32_e32 v141, 31, v140
	v_lshl_add_u64 v[134:135], s[36:37], 1, v[134:135]
	v_lshl_add_u64 v[134:135], v[140:141], 1, v[134:135]
	global_store_dwordx4 v[134:135], v[130:133], off

;     template <bool SAMPLE> __device__ __forceinline__ void body(const pg8::f32x4 (&acc)[2][2][4][2], const pg8::Unit& u, int wr, int fr, int cl0_, int acol0, LAS float* CW, LAS float* BD, LAS float* RSL) const {
;     ...
;                 const int rl = ai * 128 + wr * 64 + m * 16 + fro, row = u.pm * 256 + rl; const float rs = RSL[rl];
;                 v4u hw;
; #pragma unroll
;                 for (int n = 0; n < 2; ++n) {
;                     f32x4 cv2[2];
; #pragma unroll
;                     for (int bj = 0; bj < 2; ++bj) {
;                         const int cl = bj * 128 + cl0 + 4 * n, gcol = bj * DFF + acol0 + cl0 + 4 * n; const f32x4 x = acc[ai][bj][m][n] * rs;
;                         f32x4 s1, s2;
; #pragma unroll
;                         for (int i = 0; i < 4; ++i) { s1[i] = dpp_ror1(x[i]); s2[i] = dpp_ror2(x[i]); }
;                         if (SAMPLE) { const int t = fro & 3; const float* sp = state_conv + (size_t)((row - MP) >> 2) * 2 * UPW + gcol;
;                             const f32x4 S0 = *(const GAS f32x4*)sp, S1 = *(const GAS f32x4*)(sp + UPW);
; #pragma unroll
;                             for (int i = 0; i < 4; ++i) { s1[i] = (t >= 1) ? s1[i] : S1[i]; s2[i] = (t >= 2) ? s2[i] : (t == 1 ? S1[i] : S0[i]); }
;                             if (t >= 2) *(GAS f32x4*)(out + O_CVS + ((size_t)((row - MP) >> 2) * 2 + (t - 2)) * UPW + gcol) = x;
;                         } else if (m > 0) { const f32x4 xp = acc[ai][bj][m > 0 ? m - 1 : 0][n] * RSL[rl - 16];
; #pragma unroll
;                             for (int i = 0; i < 4; ++i) { s1[i] = dpp_ror1(fro == 15 ? xp[i] : x[i]); s2[i] = dpp_ror2(fro >= 14 ? xp[i] : x[i]); }
;                         } else { const int pb = (wr == 1) ? ai * 2 : 1;
;                             const int pr0 = (pb >> 1) * 128 + (pb & 1) * 64 + 62;
;                             const f32x4 b2 = *(const LAS f32x4*)(BD + (pb * 2 + 0) * 256 + cl) * RSL[pr0], b1 = *(const LAS f32x4*)(BD + (pb * 2 + 1) * 256 + cl) * RSL[pr0 + 1];
; #pragma unroll
;                             for (int i = 0; i < 4; ++i) { s1[i] = (fro >= 1) ? s1[i] : b1[i]; s2[i] = (fro >= 2) ? s2[i] : (fro == 1 ? b1[i] : b2[i]); }
;                         }
;                         const f32x4 w0 = *(const LAS f32x4*)(CW + cl), w1 = *(const LAS f32x4*)(CW + 256 + cl), w2 = *(const LAS f32x4*)(CW + 512 + cl), cb = *(const LAS f32x4*)(CW + 768 + cl);
.LBB0_2618:
	s_or_b64 exec, exec, s[0:1]
	v_mov_b32_e32 v140, v198
	v_lshl_add_u32 v141, v198, 2, 0
	v_cmp_eq_u32_e64 s[4:5], 15, v199
	v_cmp_lt_i32_e64 s[2:3], 13, v199
	v_add_u32_e32 v158, s90, v199
	v_add_u32_e32 v141, 0x20000, v141
	v_lshl_add_u32 v159, v158, 2, 0
	v_add_u32_e32 v159, 0x22fc0, v159
	ds_read_b32 v138, v159 offset:64
	ds_read_b32 v168, v159
	ds_read_b128 v[204:207], v141
	ds_read_b128 v[208:211], v141 offset:1024
	ds_read_b128 v[212:215], v141 offset:2048
	ds_read_b128 v[216:219], v141 offset:3072
	ds_read_b128 v[228:231], v141 offset:512
	ds_read_b128 v[232:235], v141 offset:1536
	ds_read_b128 v[236:239], v141 offset:2560
	ds_read_b128 v[240:243], v141 offset:3584
	v_add_u32_e32 v188, 0xffffff02, v158
	v_add_u32_e32 v178, s36, v198
	s_ashr_i32 s29, s28, 31
	v_readlane_b32 s6, v254, 47
	v_readlane_b32 s7, v254, 48
	v_lshl_add_u64 v[152:153], s[28:29], 1, v[188:189]
	v_ashrrev_i32_e32 v179, 31, v178
	v_add_u32_e32 v200, 0xb00, v178
	v_mov_b64_e32 v[154:155], s[6:7]
	v_ashrrev_i32_e32 v201, 31, v200
	v_mad_u64_u32 v[154:155], s[6:7], v152, s87, v[154:155]
	s_and_b32 s8, s28, 31
	v_mad_i32_i24 v155, v153, s87, v155
	s_ashr_i32 s6, s28, 5
	s_ashr_i32 s7, s6, 31
	v_lshl_add_u64 v[170:171], v[178:179], 1, v[154:155]
	v_lshl_add_u64 v[172:173], v[200:201], 1, v[154:155]
	v_lshl_add_u64 v[152:153], s[6:7], 1, v[188:189]
	v_readlane_b32 s6, v255, 39
	v_readlane_b32 s7, v255, 40
	s_nop 1
	v_mov_b64_e32 v[154:155], s[6:7]
	v_mad_u64_u32 v[154:155], s[6:7], v152, s91, v[154:155]
	v_mad_i32_i24 v155, v153, s91, v155
	v_lshl_add_u64 v[174:175], v[178:179], 2, v[154:155]
	v_lshl_add_u64 v[176:177], v[200:201], 2, v[154:155]
	s_movk_i32 s6, 0xfd
	v_cmp_lt_i32_e32 vcc, s6, v158
	ds_read_b128 v[244:247], v141 offset:16
	ds_read_b128 v[248:251], v141 offset:1040
	ds_read_b128 v[142:145], v141 offset:2064
	ds_read_b128 v[146:149], v141 offset:3088
	s_waitcnt lgkmcnt(8)
	v_pk_mul_f32 v[134:135], v[14:15], v[138:139] op_sel_hi:[1,0]
	v_pk_mul_f32 v[136:137], v[16:17], v[138:139] op_sel_hi:[1,0]
	s_and_saveexec_b64 s[0:1], vcc
	s_cbranch_execz .Lmy_u13_0
	v_cvt_pk_bf16_f32 v150, v134, v135
	v_cvt_pk_bf16_f32 v151, v136, v137
	s_nop 0
	global_store_dwordx2 v[170:171], v[150:151], off
	s_cmp_lg_u32 s8, 31
	s_cbranch_scc1 .Lmy_u13_0
	global_store_dwordx4 v[174:175], v[134:137], off
.Lmy_u13_0:
	s_or_b64 exec, exec, s[0:1]
	v_pk_mul_f32 v[150:151], v[30:31], v[168:169] op_sel_hi:[1,0]
	v_pk_mul_f32 v[152:153], v[32:33], v[168:169] op_sel_hi:[1,0]
	v_cndmask_b32_e64 v154, v134, v150, s[4:5]
	v_cndmask_b32_e64 v155, v135, v151, s[4:5]
	v_cndmask_b32_e64 v156, v136, v152, s[4:5]
	v_cndmask_b32_e64 v157, v137, v153, s[4:5]
	v_cndmask_b32_e64 v150, v134, v150, s[2:3]
	v_cndmask_b32_e64 v151, v135, v151, s[2:3]
	v_cndmask_b32_e64 v152, v136, v152, s[2:3]
	v_cndmask_b32_e64 v153, v137, v153, s[2:3]
	v_fmac_f32_dpp v216, v150, v204 row_ror:2 row_mask:0xf bank_mask:0xf
	v_fmac_f32_dpp v217, v151, v205 row_ror:2 row_mask:0xf bank_mask:0xf
	v_fmac_f32_dpp v218, v152, v206 row_ror:2 row_mask:0xf bank_mask:0xf
	v_fmac_f32_dpp v219, v153, v207 row_ror:2 row_mask:0xf bank_mask:0xf
	v_fmac_f32_dpp v216, v154, v208 row_ror:1 row_mask:0xf bank_mask:0xf
	v_fmac_f32_dpp v217, v155, v209 row_ror:1 row_mask:0xf bank_mask:0xf
	v_fmac_f32_dpp v218, v156, v210 row_ror:1 row_mask:0xf bank_mask:0xf
	v_fmac_f32_dpp v219, v157, v211 row_ror:1 row_mask:0xf bank_mask:0xf
	v_pk_fma_f32 v[160:161], v[134:135], v[212:213], v[216:217]
	v_pk_fma_f32 v[162:163], v[136:137], v[214:215], v[218:219]
	ds_read_b128 v[204:207], v141 offset:528
	ds_read_b128 v[208:211], v141 offset:1552
	ds_read_b128 v[212:215], v141 offset:2576
	ds_read_b128 v[216:219], v141 offset:3600
	s_waitcnt lgkmcnt(8)
	v_pk_mul_f32 v[134:135], v[10:11], v[138:139] op_sel_hi:[1,0]
	v_pk_mul_f32 v[136:137], v[12:13], v[138:139] op_sel_hi:[1,0]
	s_and_saveexec_b64 s[0:1], vcc
	s_cbranch_execz .Lmy_u13_1
	v_cvt_pk_bf16_f32 v150, v134, v135
	v_cvt_pk_bf16_f32 v151, v136, v137
	s_nop 0
	global_store_dwordx2 v[172:173], v[150:151], off
	s_cmp_lg_u32 s8, 31
	s_cbranch_scc1 .Lmy_u13_1
	global_store_dwordx4 v[176:177], v[134:137], off
.Lmy_u13_1:
	s_or_b64 exec, exec, s[0:1]
	v_pk_mul_f32 v[150:151], v[26:27], v[168:169] op_sel_hi:[1,0]
	v_pk_mul_f32 v[152:153], v[28:29], v[168:169] op_sel_hi:[1,0]
	v_cndmask_b32_e64 v154, v134, v150, s[4:5]
	v_cndmask_b32_e64 v155, v135, v151, s[4:5]
	v_cndmask_b32_e64 v156, v136, v152, s[4:5]
	v_cndmask_b32_e64 v157, v137, v153, s[4:5]
	v_cndmask_b32_e64 v150, v134, v150, s[2:3]
	v_cndmask_b32_e64 v151, v135, v151, s[2:3]
	v_cndmask_b32_e64 v152, v136, v152, s[2:3]
	v_cndmask_b32_e64 v153, v137, v153, s[2:3]
	v_fmac_f32_dpp v240, v150, v228 row_ror:2 row_mask:0xf bank_mask:0xf
	v_fmac_f32_dpp v241, v151, v229 row_ror:2 row_mask:0xf bank_mask:0xf
	v_fmac_f32_dpp v242, v152, v230 row_ror:2 row_mask:0xf bank_mask:0xf
	v_fmac_f32_dpp v243, v153, v231 row_ror:2 row_mask:0xf bank_mask:0xf
	v_fmac_f32_dpp v240, v154, v232 row_ror:1 row_mask:0xf bank_mask:0xf
	v_fmac_f32_dpp v241, v155, v233 row_ror:1 row_mask:0xf bank_mask:0xf
	v_fmac_f32_dpp v242, v156, v234 row_ror:1 row_mask:0xf bank_mask:0xf
	v_fmac_f32_dpp v243, v157, v235 row_ror:1 row_mask:0xf bank_mask:0xf
	v_pk_fma_f32 v[164:165], v[134:135], v[236:237], v[240:241]
	v_pk_fma_f32 v[166:167], v[136:137], v[238:239], v[242:243]
	v_pk_mul_f32 v[134:135], v[160:161], v[160:161]
	v_pk_mul_f32 v[136:137], v[162:163], v[162:163]
	v_pk_fma_f32 v[134:135], v[134:135], s[54:55], 1.0 op_sel_hi:[1,0,0]
	v_pk_mul_f32 v[150:151], v[160:161], s[56:57] op_sel_hi:[1,0]
	v_pk_fma_f32 v[136:137], v[136:137], s[54:55], 1.0 op_sel_hi:[1,0,0]
	v_pk_mul_f32 v[152:153], v[162:163], s[56:57] op_sel_hi:[1,0]
	v_pk_mul_f32 v[134:135], v[150:151], v[134:135]
	v_pk_mul_f32 v[136:137], v[152:153], v[136:137]
	v_pk_mul_f32 v[134:135], v[134:135], s[58:59] op_sel_hi:[1,0]
	v_pk_mul_f32 v[136:137], v[136:137], s[58:59] op_sel_hi:[1,0]
	v_exp_f32_e32 v134, v134
	v_exp_f32_e32 v135, v135
	v_exp_f32_e32 v136, v136
	v_exp_f32_e32 v137, v137
	v_pk_add_f32 v[134:135], v[134:135], 1.0 op_sel_hi:[1,0]
	s_nop 0
	v_pk_add_f32 v[136:137], v[136:137], 1.0 op_sel_hi:[1,0]
	v_rcp_f32_e32 v134, v134
	v_rcp_f32_e32 v135, v135
	v_rcp_f32_e32 v136, v136
	v_rcp_f32_e32 v137, v137
	v_pk_mul_f32 v[134:135], v[160:161], v[134:135]
	v_pk_mul_f32 v[136:137], v[162:163], v[136:137]
	v_pk_mul_f32 v[134:135], v[164:165], v[134:135]
	v_pk_mul_f32 v[136:137], v[166:167], v[136:137]
	s_nop 0
	v_cvt_pk_bf16_f32 v130, v134, v135
	v_cvt_pk_bf16_f32 v131, v136, v137
	s_waitcnt lgkmcnt(4)
	v_pk_mul_f32 v[134:135], v[6:7], v[138:139] op_sel_hi:[1,0]
	v_pk_mul_f32 v[136:137], v[8:9], v[138:139] op_sel_hi:[1,0]
	s_and_saveexec_b64 s[0:1], vcc
	s_cbranch_execz .Lmy_u13_2
	v_cvt_pk_bf16_f32 v150, v134, v135
	v_cvt_pk_bf16_f32 v151, v136, v137
	s_nop 0
	global_store_dwordx2 v[170:171], v[150:151], off offset:8
	s_cmp_lg_u32 s8, 31
	s_cbranch_scc1 .Lmy_u13_2
	global_store_dwordx4 v[174:175], v[134:137], off offset:16
;     template <bool SAMPLE> __device__ __forceinline__ void body(const pg8::f32x4 (&acc)[2][2][4][2], const pg8::Unit& u, int wr, int fr, int cl0_, int acol0, LAS float* CW, LAS float* BD, LAS float* RSL) const {
;     ...
;                         const int cl = bj * 128 + cl0 + 4 * n, gcol = bj * DFF + acol0 + cl0 + 4 * n; const f32x4 x = acc[ai][bj][m][n] * rs;
;                         f32x4 s1, s2;
; #pragma unroll
;                         for (int i = 0; i < 4; ++i) { s1[i] = dpp_ror1(x[i]); s2[i] = dpp_ror2(x[i]); }
;                         if (SAMPLE) { const int t = fro & 3; const float* sp = state_conv + (size_t)((row - MP) >> 2) * 2 * UPW + gcol;
;                             const f32x4 S0 = *(const GAS f32x4*)sp, S1 = *(const GAS f32x4*)(sp + UPW);
; #pragma unroll
;                             for (int i = 0; i < 4; ++i) { s1[i] = (t >= 1) ? s1[i] : S1[i]; s2[i] = (t >= 2) ? s2[i] : (t == 1 ? S1[i] : S0[i]); }
;                             if (t >= 2) *(GAS f32x4*)(out + O_CVS + ((size_t)((row - MP) >> 2) * 2 + (t - 2)) * UPW + gcol) = x;
;                         } else if (m > 0) { const f32x4 xp = acc[ai][bj][m > 0 ? m - 1 : 0][n] * RSL[rl - 16];
; #pragma unroll
;                             for (int i = 0; i < 4; ++i) { s1[i] = dpp_ror1(fro == 15 ? xp[i] : x[i]); s2[i] = dpp_ror2(fro >= 14 ? xp[i] : x[i]); }
;                         } else { const int pb = (wr == 1) ? ai * 2 : 1;
;                             const int pr0 = (pb >> 1) * 128 + (pb & 1) * 64 + 62;
;                             const f32x4 b2 = *(const LAS f32x4*)(BD + (pb * 2 + 0) * 256 + cl) * RSL[pr0], b1 = *(const LAS f32x4*)(BD + (pb * 2 + 1) * 256 + cl) * RSL[pr0 + 1];
; #pragma unroll
;                             for (int i = 0; i < 4; ++i) { s1[i] = (fro >= 1) ? s1[i] : b1[i]; s2[i] = (fro >= 2) ? s2[i] : (fro == 1 ? b1[i] : b2[i]); }
;                         }
;                         const f32x4 w0 = *(const LAS f32x4*)(CW + cl), w1 = *(const LAS f32x4*)(CW + 256 + cl), w2 = *(const LAS f32x4*)(CW + 512 + cl), cb = *(const LAS f32x4*)(CW + 768 + cl);
;                         cv2[bj] = cb + s2 * w0 + s1 * w1 + x * w2;
;                         if (!SAMPLE && ai == 0 && m == 0) { if (rl < 2) { v2u w; w.x = cvt_pk_bf16(x[0], x[1]); w.y = cvt_pk_bf16(x[2], x[3]); *(GAS v2u*)(UPF + ((size_t)u.pm * 2 + rl) * UPW + gcol) = w; } }
.Lmy_u13_2:
	s_or_b64 exec, exec, s[0:1]
	v_pk_mul_f32 v[150:151], v[22:23], v[168:169] op_sel_hi:[1,0]
	v_pk_mul_f32 v[152:153], v[24:25], v[168:169] op_sel_hi:[1,0]
	v_cndmask_b32_e64 v154, v134, v150, s[4:5]
	v_cndmask_b32_e64 v155, v135, v151, s[4:5]
	v_cndmask_b32_e64 v156, v136, v152, s[4:5]
	v_cndmask_b32_e64 v157, v137, v153, s[4:5]
	v_cndmask_b32_e64 v150, v134, v150, s[2:3]
	v_cndmask_b32_e64 v151, v135, v151, s[2:3]
	v_cndmask_b32_e64 v152, v136, v152, s[2:3]
	v_cndmask_b32_e64 v153, v137, v153, s[2:3]
	v_fmac_f32_dpp v146, v150, v244 row_ror:2 row_mask:0xf bank_mask:0xf
	v_fmac_f32_dpp v147, v151, v245 row_ror:2 row_mask:0xf bank_mask:0xf
	v_fmac_f32_dpp v148, v152, v246 row_ror:2 row_mask:0xf bank_mask:0xf
	v_fmac_f32_dpp v149, v153, v247 row_ror:2 row_mask:0xf bank_mask:0xf
	v_fmac_f32_dpp v146, v154, v248 row_ror:1 row_mask:0xf bank_mask:0xf
	v_fmac_f32_dpp v147, v155, v249 row_ror:1 row_mask:0xf bank_mask:0xf
	v_fmac_f32_dpp v148, v156, v250 row_ror:1 row_mask:0xf bank_mask:0xf
	v_fmac_f32_dpp v149, v157, v251 row_ror:1 row_mask:0xf bank_mask:0xf
	v_pk_fma_f32 v[160:161], v[134:135], v[142:143], v[146:147]
	v_pk_fma_f32 v[162:163], v[136:137], v[144:145], v[148:149]
	s_waitcnt lgkmcnt(0)
	v_pk_mul_f32 v[134:135], v[2:3], v[138:139] op_sel_hi:[1,0]
	v_pk_mul_f32 v[136:137], v[4:5], v[138:139] op_sel_hi:[1,0]
	s_and_saveexec_b64 s[0:1], vcc
	s_cbranch_execz .Lmy_u13_3
	v_cvt_pk_bf16_f32 v150, v134, v135
	v_cvt_pk_bf16_f32 v151, v136, v137
	s_nop 0
	global_store_dwordx2 v[172:173], v[150:151], off offset:8
	s_cmp_lg_u32 s8, 31
	s_cbranch_scc1 .Lmy_u13_3
	global_store_dwordx4 v[176:177], v[134:137], off offset:16
.Lmy_u13_3:
	s_or_b64 exec, exec, s[0:1]
	v_pk_mul_f32 v[150:151], v[18:19], v[168:169] op_sel_hi:[1,0]
	v_pk_mul_f32 v[152:153], v[20:21], v[168:169] op_sel_hi:[1,0]
	v_cndmask_b32_e64 v154, v134, v150, s[4:5]
	v_cndmask_b32_e64 v155, v135, v151, s[4:5]
	v_cndmask_b32_e64 v156, v136, v152, s[4:5]
	v_cndmask_b32_e64 v157, v137, v153, s[4:5]
	v_cndmask_b32_e64 v150, v134, v150, s[2:3]
	v_cndmask_b32_e64 v151, v135, v151, s[2:3]
	v_cndmask_b32_e64 v152, v136, v152, s[2:3]
	v_cndmask_b32_e64 v153, v137, v153, s[2:3]
	v_fmac_f32_dpp v216, v150, v204 row_ror:2 row_mask:0xf bank_mask:0xf
	v_fmac_f32_dpp v217, v151, v205 row_ror:2 row_mask:0xf bank_mask:0xf
	v_fmac_f32_dpp v218, v152, v206 row_ror:2 row_mask:0xf bank_mask:0xf
	v_fmac_f32_dpp v219, v153, v207 row_ror:2 row_mask:0xf bank_mask:0xf
	v_fmac_f32_dpp v216, v154, v208 row_ror:1 row_mask:0xf bank_mask:0xf
	v_fmac_f32_dpp v217, v155, v209 row_ror:1 row_mask:0xf bank_mask:0xf
	v_fmac_f32_dpp v218, v156, v210 row_ror:1 row_mask:0xf bank_mask:0xf
	v_fmac_f32_dpp v219, v157, v211 row_ror:1 row_mask:0xf bank_mask:0xf
	v_pk_fma_f32 v[164:165], v[134:135], v[212:213], v[216:217]
	v_pk_fma_f32 v[166:167], v[136:137], v[214:215], v[218:219]
	v_pk_mul_f32 v[134:135], v[160:161], v[160:161]
	v_pk_mul_f32 v[136:137], v[162:163], v[162:163]
	v_pk_fma_f32 v[134:135], v[134:135], s[54:55], 1.0 op_sel_hi:[1,0,0]
	v_pk_mul_f32 v[150:151], v[160:161], s[56:57] op_sel_hi:[1,0]
	v_pk_fma_f32 v[136:137], v[136:137], s[54:55], 1.0 op_sel_hi:[1,0,0]
	v_pk_mul_f32 v[152:153], v[162:163], s[56:57] op_sel_hi:[1,0]
	v_pk_mul_f32 v[134:135], v[150:151], v[134:135]
	v_pk_mul_f32 v[136:137], v[152:153], v[136:137]
	v_pk_mul_f32 v[134:135], v[134:135], s[58:59] op_sel_hi:[1,0]
	v_pk_mul_f32 v[136:137], v[136:137], s[58:59] op_sel_hi:[1,0]
	v_exp_f32_e32 v134, v134
	v_exp_f32_e32 v135, v135
	v_exp_f32_e32 v136, v136
	v_exp_f32_e32 v137, v137
	v_pk_add_f32 v[134:135], v[134:135], 1.0 op_sel_hi:[1,0]
	s_nop 0
	v_pk_add_f32 v[136:137], v[136:137], 1.0 op_sel_hi:[1,0]
	v_rcp_f32_e32 v134, v134
	v_rcp_f32_e32 v135, v135
	v_rcp_f32_e32 v136, v136
	v_rcp_f32_e32 v137, v137
	v_pk_mul_f32 v[134:135], v[160:161], v[134:135]
	v_pk_mul_f32 v[136:137], v[162:163], v[136:137]
	v_pk_mul_f32 v[134:135], v[164:165], v[134:135]
	v_pk_mul_f32 v[136:137], v[166:167], v[136:137]
	s_nop 0
	v_cvt_pk_bf16_f32 v132, v134, v135
	v_cvt_pk_bf16_f32 v133, v136, v137
	v_cmp_lt_i32_e32 vcc, 1, v158
	s_and_saveexec_b64 s[0:1], vcc
	s_cbranch_execz .LBB0_2632
	v_add_u32_e32 v136, s16, v158
	v_mov_b64_e32 v[134:135], s[50:51]
	v_mad_i64_i32 v[134:135], s[2:3], v136, s82, v[134:135]
	v_ashrrev_i32_e32 v141, 31, v140
	v_lshl_add_u64 v[134:135], s[36:37], 1, v[134:135]
	v_lshl_add_u64 v[134:135], v[140:141], 1, v[134:135]
	global_store_dwordx4 v[134:135], v[130:133], off
